# lru_pass1: 4-step ds_bpermute affine scan replaced by in-place DPP row_shr fmac/mul (64 DPP ops instead of 192 scan instructions)
# baseline (speedup 1.0000x reference)
; __device__ __forceinline__ float fexp(float x) { return __builtin_amdgcn_exp2f(x * 1.4426950408889634f); }
; __device__ __forceinline__ unsigned pk2(float lo, float hi) { unsigned r; asm("v_cvt_pk_bf16_f32 %0, %1, %2" : "=v"(r) : "v"(lo), "v"(hi)); return r; }
; __device__ __forceinline__ float bflo(unsigned w) { return __uint_as_float(w << 16); }
; __device__ __forceinline__ float bfhi(unsigned w) { return __uint_as_float(w & 0xffff0000u); }
; __device__ __forceinline__ float sigmoidf_(float x) { return __builtin_amdgcn_rcpf(1.f + fexp(-x)); }
; __device__ __forceinline__ f32x4 mfma16(bf16x8 a, bf16x8 b, f32x4 c) { return __builtin_amdgcn_mfma_f32_16x16x32_bf16(a, b, c, 0, 0, 0); }
; template <int PASS>
; __device__ __forceinline__ void lru_pass(CArgs& a, int l, int panel) {
;     ...
;         float xc[8];
; #pragma unroll
;         for (int c = 0; c < 8; ++c) xc[c] = cb[c];
; #pragma unroll
;         for (int j = 0; j < 4; ++j) {
;             const u32x4 xv = xn[j];
; #pragma unroll
;             for (int k = 0; k < 4; ++k) { xc[2 * k] += cw[j][2 * k] * bflo(xv[k]); xc[2 * k + 1] += cw[j][2 * k + 1] * bfhi(xv[k]); }
;         }
;         const u32x4 gv = gn;
;         if (tile + 1 < 16) LRU_LOAD(tile + 1);
;         u32x4 xp; xp.x = pk2(xc[0], xc[1]); xp.y = pk2(xc[2], xc[3]); xp.z = pk2(xc[4], xc[5]); xp.w = pk2(xc[6], xc[7]);
;         const bf16x8 xcb = __builtin_bit_cast(bf16x8, xp);
;         f32x4 ar[2], ai[2];
; #pragma unroll
;         for (int mt = 0; mt < 2; ++mt) { ar[mt] = mfma16(wrf[mt], xcb, (f32x4){0.f, 0.f, 0.f, 0.f}); ai[mt] = mfma16(wif[mt], xcb, (f32x4){0.f, 0.f, 0.f, 0.f}); }
;         float A[8], B[8];
; #pragma unroll
;         for (int c = 0; c < 8; ++c) {
;             const float gr = sigmoidf_(ar[c >> 2][c & 3] + br[c]), gi = sigmoidf_(ai[c >> 2][c & 3] + bi[c]);
;             const float la = -gr * sp[c];
;             const float x2 = 2.f * la;
;             const float om = -x2 * (1.f + x2 * (0.5f + x2 * (0.16666667f + x2 * (0.041666668f + x2 * (0.0083333338f + x2 * 0.0013888889f)))));
;             A[c] = fexp(la); B[c] = __builtin_amdgcn_sqrtf(fmaxf(om, 0.f)) * (gi * xc[c]);
;         }
.LBB0_211:
	v_lshlrev_b32_e32 v138, 16, v76
	v_and_b32_e32 v139, 0xffff0000, v76
	v_lshlrev_b32_e32 v76, 16, v77
	v_and_b32_e32 v77, 0xffff0000, v77
	v_lshlrev_b32_e32 v140, 16, v80
	v_and_b32_e32 v141, 0xffff0000, v80
	v_pk_fma_f32 v[76:77], v[26:27], v[76:77], v[58:59]
	v_lshlrev_b32_e32 v80, 16, v81
	v_and_b32_e32 v81, 0xffff0000, v81
	v_pk_fma_f32 v[76:77], v[34:35], v[80:81], v[76:77]
	v_lshlrev_b32_e32 v80, 16, v85
	v_and_b32_e32 v81, 0xffff0000, v85
	v_pk_fma_f32 v[76:77], v[42:43], v[80:81], v[76:77]
	v_lshlrev_b32_e32 v80, 16, v121
	v_and_b32_e32 v81, 0xffff0000, v121
	v_pk_fma_f32 v[144:145], v[50:51], v[80:81], v[76:77]
	v_lshlrev_b32_e32 v76, 16, v78
	v_and_b32_e32 v77, 0xffff0000, v78
	v_pk_fma_f32 v[76:77], v[20:21], v[76:77], v[52:53]
	v_lshlrev_b32_e32 v80, 16, v82
	v_and_b32_e32 v81, 0xffff0000, v82
	v_pk_fma_f32 v[76:77], v[28:29], v[80:81], v[76:77]
	v_lshlrev_b32_e32 v80, 16, v86
	v_and_b32_e32 v81, 0xffff0000, v86
	v_pk_fma_f32 v[76:77], v[36:37], v[80:81], v[76:77]
	v_lshlrev_b32_e32 v80, 16, v122
	v_and_b32_e32 v81, 0xffff0000, v122
	v_pk_fma_f32 v[146:147], v[44:45], v[80:81], v[76:77]
	v_lshlrev_b32_e32 v76, 16, v79
	v_and_b32_e32 v77, 0xffff0000, v79
	v_pk_fma_f32 v[138:139], v[24:25], v[138:139], v[56:57]
	v_pk_fma_f32 v[76:77], v[22:23], v[76:77], v[54:55]
	v_lshlrev_b32_e32 v78, 16, v83
	v_and_b32_e32 v79, 0xffff0000, v83
	v_pk_fma_f32 v[138:139], v[32:33], v[140:141], v[138:139]
	v_lshlrev_b32_e32 v140, 16, v84
	v_and_b32_e32 v141, 0xffff0000, v84
	v_pk_fma_f32 v[76:77], v[30:31], v[78:79], v[76:77]
	v_lshlrev_b32_e32 v78, 16, v87
	v_and_b32_e32 v79, 0xffff0000, v87
	v_pk_fma_f32 v[138:139], v[40:41], v[140:141], v[138:139]
	v_lshlrev_b32_e32 v140, 16, v120
	v_and_b32_e32 v141, 0xffff0000, v120
	v_pk_fma_f32 v[76:77], v[38:39], v[78:79], v[76:77]
	v_lshlrev_b32_e32 v78, 16, v123
	v_and_b32_e32 v79, 0xffff0000, v123
	v_pk_fma_f32 v[142:143], v[48:49], v[140:141], v[138:139]
	v_pk_fma_f32 v[76:77], v[46:47], v[78:79], v[76:77]
	v_cvt_pk_bf16_f32 v78, v142, v143
	v_cvt_pk_bf16_f32 v79, v144, v145
	v_cvt_pk_bf16_f32 v80, v146, v147
	s_nop 0
	v_cvt_pk_bf16_f32 v81, v76, v77
	s_nop 0
	v_mfma_f32_16x16x32_bf16 v[82:85], v[60:63], v[78:81], 0
	v_mfma_f32_16x16x32_bf16 v[120:123], v[68:71], v[78:81], 0
	v_mfma_f32_16x16x32_bf16 v[138:141], v[64:67], v[78:81], 0
	s_nop 5
	v_add_f32_e32 v0, v8, v82
	v_mul_f32_e32 v0, 0xbfb8aa3b, v0
	v_exp_f32_e32 v0, v0
	v_add_f32_e32 v83, v9, v83
	v_mul_f32_e32 v83, 0xbfb8aa3b, v83
	v_exp_f32_e32 v83, v83
	v_add_f32_e32 v0, 1.0, v0
	v_rcp_f32_e64 v0, -v0
	v_add_f32_e32 v82, v16, v120
	v_add_f32_e32 v83, 1.0, v83
	v_rcp_f32_e64 v120, -v83
	v_mul_f32_e32 v0, v130, v0
	v_add_f32_e32 v86, v0, v0
	v_fmamk_f32 v87, v86, 0x3ab60b61, v229
	v_fmaak_f32 v87, v86, v87, 0x3d2aaaab
	v_fmaak_f32 v87, v86, v87, 0x3e2aaaab
	v_fma_f32 v87, v86, v87, 0.5
	v_fma_f32 v87, v86, v87, 1.0
	v_mul_f32_e64 v86, v87, -v86
	v_add_f32_e32 v87, v17, v121
	v_mul_f32_e32 v87, 0xbfb8aa3b, v87
	v_exp_f32_e32 v87, v87
	v_mul_f32_e32 v82, 0xbfb8aa3b, v82
	v_add_f32_e32 v84, v10, v84
	v_exp_f32_e32 v82, v82
	v_add_f32_e32 v83, 1.0, v87
	v_mul_f32_e32 v87, v131, v120
	v_add_f32_e32 v120, v87, v87
	v_fmamk_f32 v121, v120, 0x3ab60b61, v229
	v_fmaak_f32 v121, v120, v121, 0x3d2aaaab
	v_mul_f32_e32 v84, 0xbfb8aa3b, v84
	v_fmaak_f32 v121, v120, v121, 0x3e2aaaab
	v_exp_f32_e32 v84, v84
	v_fma_f32 v121, v120, v121, 0.5
	v_fma_f32 v121, v120, v121, 1.0
	v_add_f32_e32 v82, 1.0, v82
	v_mul_f32_e64 v120, v121, -v120
	v_mul_f32_e32 v87, 0x3fb8aa3b, v87
	v_rcp_f32_e32 v82, v82
	v_max_f32_e32 v86, 0, v86
	v_rcp_f32_e32 v83, v83
	v_exp_f32_e32 v121, v87
	v_max_f32_e32 v87, 0, v120
	v_add_f32_e32 v84, 1.0, v84
	v_sqrt_f32_e32 v86, v86
	v_sqrt_f32_e32 v87, v87
	v_add_f32_e32 v120, v18, v122
	v_rcp_f32_e64 v122, -v84
	v_mul_f32_e32 v120, 0xbfb8aa3b, v120
	v_exp_f32_e32 v120, v120
	v_pk_mul_f32 v[82:83], v[142:143], v[82:83]
	v_add_f32_e32 v85, v11, v85
	v_pk_mul_f32 v[82:83], v[82:83], v[86:87]
	v_mul_f32_e32 v86, v132, v122
	v_add_f32_e32 v87, v86, v86
	v_add_f32_e32 v84, 1.0, v120
	v_fmamk_f32 v120, v87, 0x3ab60b61, v229
	v_fmaak_f32 v120, v87, v120, 0x3d2aaaab
	v_fmaak_f32 v120, v87, v120, 0x3e2aaaab
	v_mul_f32_e32 v85, 0xbfb8aa3b, v85
	v_fma_f32 v120, v87, v120, 0.5
	v_exp_f32_e32 v85, v85
	v_fma_f32 v120, v87, v120, 1.0
	v_mul_f32_e64 v87, v120, -v87
	v_mul_f32_e32 v86, 0x3fb8aa3b, v86
	v_exp_f32_e32 v120, v86
	v_max_f32_e32 v86, 0, v87
	v_add_f32_e32 v87, v19, v123
	v_mul_f32_e32 v87, 0xbfb8aa3b, v87
	v_add_f32_e32 v85, 1.0, v85
	v_exp_f32_e32 v87, v87
	v_rcp_f32_e64 v122, -v85
	v_rcp_f32_e32 v84, v84
	v_sqrt_f32_e32 v86, v86
	v_add_f32_e32 v85, 1.0, v87
	v_mul_f32_e32 v87, v133, v122
	v_add_f32_e32 v122, v87, v87
	v_fmamk_f32 v123, v122, 0x3ab60b61, v229
	v_fmaak_f32 v123, v122, v123, 0x3d2aaaab
	v_fmaak_f32 v123, v122, v123, 0x3e2aaaab
	v_fma_f32 v123, v122, v123, 0.5
	v_fma_f32 v123, v122, v123, 1.0
	v_mul_f32_e64 v122, v123, -v122
	v_mul_f32_e32 v87, 0x3fb8aa3b, v87
	v_exp_f32_e32 v123, v87
	v_max_f32_e32 v87, 0, v122
	v_add_f32_e32 v122, v4, v138
	v_mul_f32_e32 v122, 0xbfb8aa3b, v122
	v_exp_f32_e32 v122, v122
	v_rcp_f32_e32 v85, v85
	v_sqrt_f32_e32 v87, v87
	v_mfma_f32_16x16x32_bf16 v[78:81], v[72:75], v[78:81], 0
	v_add_f32_e32 v122, 1.0, v122
	v_rcp_f32_e64 v122, -v122
	v_pk_mul_f32 v[84:85], v[144:145], v[84:85]
	v_mul_f32_e32 v0, 0x3fb8aa3b, v0
	v_pk_mul_f32 v[84:85], v[84:85], v[86:87]
	v_mul_f32_e32 v86, v134, v122
	v_add_f32_e32 v87, v86, v86
	v_fmamk_f32 v122, v87, 0x3ab60b61, v229
	v_fmaak_f32 v122, v87, v122, 0x3d2aaaab
	v_fmaak_f32 v122, v87, v122, 0x3e2aaaab
	v_fma_f32 v122, v87, v122, 0.5
	v_fma_f32 v122, v87, v122, 1.0
; __device__ __forceinline__ float fexp(float x) { return __builtin_amdgcn_exp2f(x * 1.4426950408889634f); }
; __device__ __forceinline__ float sigmoidf_(float x) { return __builtin_amdgcn_rcpf(1.f + fexp(-x)); }
; template <int PASS>
; __device__ __forceinline__ void lru_pass(CArgs& a, int l, int panel) {
;     ...
;         for (int c = 0; c < 8; ++c) {
;             const float gr = sigmoidf_(ar[c >> 2][c & 3] + br[c]), gi = sigmoidf_(ai[c >> 2][c & 3] + bi[c]);
;             const float la = -gr * sp[c];
;             const float x2 = 2.f * la;
;             const float om = -x2 * (1.f + x2 * (0.5f + x2 * (0.16666667f + x2 * (0.041666668f + x2 * (0.0083333338f + x2 * 0.0013888889f)))));
;             A[c] = fexp(la); B[c] = __builtin_amdgcn_sqrtf(fmaxf(om, 0.f)) * (gi * xc[c]);
;         }
; #pragma unroll
;         for (int s = 1; s < 16; s <<= 1) {
; #pragma unroll
;             for (int c = 0; c < 8; ++c) { const float ap = __shfl_up(A[c], s, 16), bp = __shfl_up(B[c], s, 16);
;                 if (fr >= s) { B[c] = A[c] * bp + B[c]; A[c] = A[c] * ap; } }
;         }
	v_mul_f32_e64 v87, v122, -v87
	v_mul_f32_e32 v86, 0x3fb8aa3b, v86
	v_exp_f32_e32 v122, v86
	v_max_f32_e32 v86, 0, v87
	v_add_f32_e32 v87, v5, v139
	v_mul_f32_e32 v87, 0xbfb8aa3b, v87
	v_exp_f32_e32 v87, v87
	v_add_f32_e32 v78, v12, v78
	v_add_f32_e32 v79, v13, v79
	v_mul_f32_e32 v78, 0xbfb8aa3b, v78
	v_add_f32_e32 v87, 1.0, v87
	v_rcp_f32_e64 v87, -v87
	v_mul_f32_e32 v79, 0xbfb8aa3b, v79
	v_exp_f32_e32 v78, v78
	v_exp_f32_e32 v79, v79
	v_mul_f32_e32 v87, v135, v87
	v_add_f32_e32 v138, v87, v87
	v_fmamk_f32 v139, v138, 0x3ab60b61, v229
	v_fmaak_f32 v139, v138, v139, 0x3d2aaaab
	v_fmaak_f32 v139, v138, v139, 0x3e2aaaab
	v_fma_f32 v139, v138, v139, 0.5
	v_fma_f32 v139, v138, v139, 1.0
	v_mul_f32_e64 v138, v139, -v138
	v_mul_f32_e32 v87, 0x3fb8aa3b, v87
	v_exp_f32_e32 v139, v87
	v_max_f32_e32 v87, 0, v138
	v_add_f32_e32 v138, v6, v140
	v_mul_f32_e32 v138, 0xbfb8aa3b, v138
	v_exp_f32_e32 v138, v138
	v_add_f32_e32 v78, 1.0, v78
	v_add_f32_e32 v79, 1.0, v79
	v_rcp_f32_e32 v78, v78
	v_rcp_f32_e32 v79, v79
	v_add_f32_e32 v138, 1.0, v138
	v_sqrt_f32_e32 v86, v86
	v_sqrt_f32_e32 v87, v87
	v_rcp_f32_e64 v138, -v138
	v_pk_mul_f32 v[78:79], v[146:147], v[78:79]
	v_add_f32_e32 v80, v14, v80
	v_pk_mul_f32 v[78:79], v[78:79], v[86:87]
	v_mul_f32_e32 v86, v136, v138
	v_add_f32_e32 v87, v86, v86
	v_fmamk_f32 v138, v87, 0x3ab60b61, v229
	v_fmaak_f32 v138, v87, v138, 0x3d2aaaab
	v_fmaak_f32 v138, v87, v138, 0x3e2aaaab
	v_fma_f32 v138, v87, v138, 0.5
	v_fma_f32 v138, v87, v138, 1.0
	v_mul_f32_e64 v87, v138, -v87
	v_mul_f32_e32 v86, 0x3fb8aa3b, v86
	v_exp_f32_e32 v138, v86
	v_max_f32_e32 v86, 0, v87
	v_add_f32_e32 v87, v7, v141
	v_mul_f32_e32 v87, 0xbfb8aa3b, v87
	v_exp_f32_e32 v87, v87
	v_add_f32_e32 v81, v15, v81
	v_mul_f32_e32 v80, 0xbfb8aa3b, v80
	v_mul_f32_e32 v81, 0xbfb8aa3b, v81
	v_add_f32_e32 v87, 1.0, v87
	v_rcp_f32_e64 v87, -v87
	v_exp_f32_e32 v80, v80
	v_exp_f32_e32 v81, v81
	v_exp_f32_e32 v0, v0
	v_mul_f32_e32 v87, v137, v87
	v_add_f32_e32 v140, v87, v87
	v_fmamk_f32 v141, v140, 0x3ab60b61, v229
	v_fmaak_f32 v141, v140, v141, 0x3d2aaaab
	v_fmaak_f32 v141, v140, v141, 0x3e2aaaab
	v_fma_f32 v141, v140, v141, 0.5
	v_fma_f32 v141, v140, v141, 1.0
	v_add_f32_e32 v80, 1.0, v80
	v_add_f32_e32 v81, 1.0, v81
	v_mul_f32_e64 v140, v141, -v140
	v_rcp_f32_e32 v80, v80
	v_rcp_f32_e32 v81, v81
	v_mul_f32_e32 v141, 0x3fb8aa3b, v87
	v_max_f32_e32 v87, 0, v140
	v_sqrt_f32_e32 v86, v86
	v_sqrt_f32_e32 v87, v87
	v_exp_f32_e32 v141, v141
	v_pk_mul_f32 v[76:77], v[76:77], v[80:81]
	v_pk_mul_f32 v[76:77], v[76:77], v[86:87]
	s_waitcnt lgkmcnt(8)
	s_waitcnt lgkmcnt(8)
	s_waitcnt lgkmcnt(9)
	s_waitcnt lgkmcnt(8)
	s_waitcnt lgkmcnt(7)
	s_waitcnt lgkmcnt(6)
	s_waitcnt lgkmcnt(5)
	s_waitcnt lgkmcnt(4)
	s_waitcnt lgkmcnt(3)
	s_waitcnt lgkmcnt(8)
	s_waitcnt lgkmcnt(7)
	s_waitcnt lgkmcnt(8)
	s_waitcnt lgkmcnt(8)
	s_waitcnt lgkmcnt(9)
	s_nop 1
	v_fmac_f32_dpp v82, v82, v0 row_shr:1 row_mask:0xf bank_mask:0xf
	v_fmac_f32_dpp v83, v83, v121 row_shr:1 row_mask:0xf bank_mask:0xf
	v_fmac_f32_dpp v77, v77, v141 row_shr:1 row_mask:0xf bank_mask:0xf
	v_fmac_f32_dpp v79, v79, v139 row_shr:1 row_mask:0xf bank_mask:0xf
	v_fmac_f32_dpp v84, v84, v120 row_shr:1 row_mask:0xf bank_mask:0xf
	v_fmac_f32_dpp v76, v76, v138 row_shr:1 row_mask:0xf bank_mask:0xf
	v_fmac_f32_dpp v78, v78, v122 row_shr:1 row_mask:0xf bank_mask:0xf
	v_fmac_f32_dpp v85, v85, v123 row_shr:1 row_mask:0xf bank_mask:0xf
	s_nop 0
	v_mul_f32_dpp v0, v0, v0 row_shr:1 row_mask:0xf bank_mask:0xf
	v_mul_f32_dpp v121, v121, v121 row_shr:1 row_mask:0xf bank_mask:0xf
	v_mul_f32_dpp v141, v141, v141 row_shr:1 row_mask:0xf bank_mask:0xf
	v_mul_f32_dpp v139, v139, v139 row_shr:1 row_mask:0xf bank_mask:0xf
	v_mul_f32_dpp v120, v120, v120 row_shr:1 row_mask:0xf bank_mask:0xf
	v_mul_f32_dpp v138, v138, v138 row_shr:1 row_mask:0xf bank_mask:0xf
	v_mul_f32_dpp v122, v122, v122 row_shr:1 row_mask:0xf bank_mask:0xf
	v_mul_f32_dpp v123, v123, v123 row_shr:1 row_mask:0xf bank_mask:0xf
	s_nop 1
	v_fmac_f32_dpp v82, v82, v0 row_shr:2 row_mask:0xf bank_mask:0xf
	v_fmac_f32_dpp v83, v83, v121 row_shr:2 row_mask:0xf bank_mask:0xf
	v_fmac_f32_dpp v77, v77, v141 row_shr:2 row_mask:0xf bank_mask:0xf
	v_fmac_f32_dpp v79, v79, v139 row_shr:2 row_mask:0xf bank_mask:0xf
	v_fmac_f32_dpp v84, v84, v120 row_shr:2 row_mask:0xf bank_mask:0xf
	v_fmac_f32_dpp v76, v76, v138 row_shr:2 row_mask:0xf bank_mask:0xf
	v_fmac_f32_dpp v78, v78, v122 row_shr:2 row_mask:0xf bank_mask:0xf
	v_fmac_f32_dpp v85, v85, v123 row_shr:2 row_mask:0xf bank_mask:0xf
	s_nop 0
	v_mul_f32_dpp v0, v0, v0 row_shr:2 row_mask:0xf bank_mask:0xf
	v_mul_f32_dpp v121, v121, v121 row_shr:2 row_mask:0xf bank_mask:0xf
	v_mul_f32_dpp v141, v141, v141 row_shr:2 row_mask:0xf bank_mask:0xf
	v_mul_f32_dpp v139, v139, v139 row_shr:2 row_mask:0xf bank_mask:0xf
	v_mul_f32_dpp v120, v120, v120 row_shr:2 row_mask:0xf bank_mask:0xf
	v_mul_f32_dpp v138, v138, v138 row_shr:2 row_mask:0xf bank_mask:0xf
	v_mul_f32_dpp v122, v122, v122 row_shr:2 row_mask:0xf bank_mask:0xf
; __device__ __forceinline__ unsigned pk2(float lo, float hi) { unsigned r; asm("v_cvt_pk_bf16_f32 %0, %1, %2" : "=v"(r) : "v"(lo), "v"(hi)); return r; }
; __device__ __forceinline__ float bflo(unsigned w) { return __uint_as_float(w << 16); }
; __device__ __forceinline__ float bfhi(unsigned w) { return __uint_as_float(w & 0xffff0000u); }
; __device__ __forceinline__ float gelu_tanh(float x) { const float u = 0.7978845608028654f * (x + 0.044715f * x * x * x); return x * __builtin_amdgcn_rcpf(1.f + fexp(-2.f * u)); }
; template <int PASS>
; __device__ __forceinline__ void lru_pass(CArgs& a, int l, int panel) {
;     ...
;         for (int s = 1; s < 16; s <<= 1) {
; #pragma unroll
;             for (int c = 0; c < 8; ++c) { const float ap = __shfl_up(A[c], s, 16), bp = __shfl_up(B[c], s, 16);
;                 if (fr >= s) { B[c] = A[c] * bp + B[c]; A[c] = A[c] * ap; } }
;         }
;         if (PASS == 2) {
;             float o[8];
; #pragma unroll
;             for (int k = 0; k < 4; ++k) { o[2 * k] = (A[2 * k] * hin[2 * k] + B[2 * k]) * gelu_tanh(bflo(gv[k])); o[2 * k + 1] = (A[2 * k + 1] * hin[2 * k + 1] + B[2 * k + 1]) * gelu_tanh(bfhi(gv[k])); }
;             u32x4 w; w.x = pk2(o[0], o[1]); w.y = pk2(o[2], o[3]); w.z = pk2(o[4], o[5]); w.w = pk2(o[6], o[7]);
;             *(u32x4*)(MIX + (size_t)t * 2048 + (768 + ch0) * 2) = w;
;         }
;         if (PASS == 1) {
;             u32x4 w0, w1; w0.x = pk2(A[0], B[0]); w0.y = pk2(A[1], B[1]); w0.z = pk2(A[2], B[2]); w0.w = pk2(A[3], B[3]); w1.x = pk2(A[4], B[4]); w1.y = pk2(A[5], B[5]); w1.z = pk2(A[6], B[6]); w1.w = pk2(A[7], B[7]);
;             u32x4* abp = (u32x4*)(ws + WS_LRUAB + (((size_t)panel * 256 + t) * 256 + ch0) * 4); abp[0] = w0; abp[1] = w1;
;         }
;         float a15[8], b15[8];
; #pragma unroll
;         for (int c = 0; c < 8; ++c) { a15[c] = A[c]; b15[c] = B[c]; hin[c] = a15[c] * hin[c] + b15[c]; atot[c] *= a15[c]; }
;         if (PASS == 1 && fr == 15) {
;             f32x4* cp = (f32x4*)(ws + WS_LRUC + (((size_t)panel * 16 + tile) * 256 + ch0) * 8);
;             cp[0] = (f32x4){a15[0], b15[0], a15[1], b15[1]}; cp[1] = (f32x4){a15[2], b15[2], a15[3], b15[3]}; cp[2] = (f32x4){a15[4], b15[4], a15[5], b15[5]}; cp[3] = (f32x4){a15[6], b15[6], a15[7], b15[7]};
	v_mul_f32_dpp v123, v123, v123 row_shr:2 row_mask:0xf bank_mask:0xf
	s_nop 1
	v_fmac_f32_dpp v82, v82, v0 row_shr:4 row_mask:0xf bank_mask:0xf
	v_fmac_f32_dpp v83, v83, v121 row_shr:4 row_mask:0xf bank_mask:0xf
	v_fmac_f32_dpp v77, v77, v141 row_shr:4 row_mask:0xf bank_mask:0xf
	v_fmac_f32_dpp v79, v79, v139 row_shr:4 row_mask:0xf bank_mask:0xf
	v_fmac_f32_dpp v84, v84, v120 row_shr:4 row_mask:0xf bank_mask:0xf
	v_fmac_f32_dpp v76, v76, v138 row_shr:4 row_mask:0xf bank_mask:0xf
	v_fmac_f32_dpp v78, v78, v122 row_shr:4 row_mask:0xf bank_mask:0xf
	v_fmac_f32_dpp v85, v85, v123 row_shr:4 row_mask:0xf bank_mask:0xf
	s_nop 0
	v_mul_f32_dpp v0, v0, v0 row_shr:4 row_mask:0xf bank_mask:0xf
	v_mul_f32_dpp v121, v121, v121 row_shr:4 row_mask:0xf bank_mask:0xf
	v_mul_f32_dpp v141, v141, v141 row_shr:4 row_mask:0xf bank_mask:0xf
	v_mul_f32_dpp v139, v139, v139 row_shr:4 row_mask:0xf bank_mask:0xf
	v_mul_f32_dpp v120, v120, v120 row_shr:4 row_mask:0xf bank_mask:0xf
	v_mul_f32_dpp v138, v138, v138 row_shr:4 row_mask:0xf bank_mask:0xf
	v_mul_f32_dpp v122, v122, v122 row_shr:4 row_mask:0xf bank_mask:0xf
	v_mul_f32_dpp v123, v123, v123 row_shr:4 row_mask:0xf bank_mask:0xf
	s_nop 1
	v_fmac_f32_dpp v82, v82, v0 row_shr:8 row_mask:0xf bank_mask:0xf
	v_fmac_f32_dpp v83, v83, v121 row_shr:8 row_mask:0xf bank_mask:0xf
	v_fmac_f32_dpp v77, v77, v141 row_shr:8 row_mask:0xf bank_mask:0xf
	v_fmac_f32_dpp v79, v79, v139 row_shr:8 row_mask:0xf bank_mask:0xf
	v_fmac_f32_dpp v84, v84, v120 row_shr:8 row_mask:0xf bank_mask:0xf
	v_fmac_f32_dpp v76, v76, v138 row_shr:8 row_mask:0xf bank_mask:0xf
	v_fmac_f32_dpp v78, v78, v122 row_shr:8 row_mask:0xf bank_mask:0xf
	v_fmac_f32_dpp v85, v85, v123 row_shr:8 row_mask:0xf bank_mask:0xf
	s_nop 0
	v_mul_f32_dpp v0, v0, v0 row_shr:8 row_mask:0xf bank_mask:0xf
	v_mul_f32_dpp v121, v121, v121 row_shr:8 row_mask:0xf bank_mask:0xf
	v_mul_f32_dpp v141, v141, v141 row_shr:8 row_mask:0xf bank_mask:0xf
	v_mul_f32_dpp v139, v139, v139 row_shr:8 row_mask:0xf bank_mask:0xf
	v_mul_f32_dpp v120, v120, v120 row_shr:8 row_mask:0xf bank_mask:0xf
	v_mul_f32_dpp v138, v138, v138 row_shr:8 row_mask:0xf bank_mask:0xf
	v_mul_f32_dpp v122, v122, v122 row_shr:8 row_mask:0xf bank_mask:0xf
	v_mul_f32_dpp v123, v123, v123 row_shr:8 row_mask:0xf bank_mask:0xf
	s_nop 1
	s_waitcnt lgkmcnt(12)
	s_waitcnt lgkmcnt(11)
	s_waitcnt lgkmcnt(10)
	s_waitcnt lgkmcnt(10)
	s_waitcnt lgkmcnt(11)
	s_waitcnt lgkmcnt(10)
	s_waitcnt lgkmcnt(10)
	s_waitcnt lgkmcnt(10)
	s_waitcnt lgkmcnt(9)
	s_waitcnt lgkmcnt(8)
	s_waitcnt lgkmcnt(9)
	s_waitcnt lgkmcnt(8)
	s_waitcnt lgkmcnt(8)
	s_waitcnt lgkmcnt(7)
	s_waitcnt lgkmcnt(6)
	s_waitcnt lgkmcnt(7)
	s_waitcnt lgkmcnt(10)
	s_waitcnt lgkmcnt(10)
	s_waitcnt lgkmcnt(11)
	s_waitcnt lgkmcnt(10)
	s_waitcnt lgkmcnt(9)
	s_waitcnt lgkmcnt(8)
	s_waitcnt lgkmcnt(7)
	s_waitcnt lgkmcnt(6)
	s_waitcnt lgkmcnt(7)
	s_waitcnt lgkmcnt(6)
	s_waitcnt lgkmcnt(6)
	s_waitcnt lgkmcnt(5)
	s_waitcnt lgkmcnt(4)
	s_waitcnt lgkmcnt(5)
	s_waitcnt lgkmcnt(7)
	s_waitcnt lgkmcnt(6)
	s_waitcnt lgkmcnt(6)
	s_waitcnt lgkmcnt(6)
	s_waitcnt lgkmcnt(5)
	s_waitcnt lgkmcnt(4)
	s_waitcnt lgkmcnt(5)
	s_waitcnt lgkmcnt(4)
	s_waitcnt lgkmcnt(3)
	s_waitcnt lgkmcnt(4)
	s_waitcnt lgkmcnt(4)
	s_waitcnt lgkmcnt(3)
	s_waitcnt lgkmcnt(7)
	s_waitcnt lgkmcnt(6)
	v_lshl_add_u64 v[146:147], s[10:11], 0, v[126:127]
	s_waitcnt lgkmcnt(5)
	s_waitcnt lgkmcnt(4)
	s_waitcnt lgkmcnt(3)
	s_waitcnt lgkmcnt(2)
	s_waitcnt lgkmcnt(1)
	s_waitcnt lgkmcnt(0)
	v_add_co_u32_e32 v146, vcc, 0x2e000000, v146
	v_mov_b32_e32 v81, v141
	v_mov_b32_e32 v80, v138
	v_mov_b32_e32 v86, v82
	v_mov_b32_e32 v87, v83
	v_mov_b32_e32 v82, v84
	v_mov_b32_e32 v83, v85
	v_mov_b32_e32 v85, v139
	v_mov_b32_e32 v84, v122
	v_mov_b32_e32 v122, v0
	v_swap_b32 v123, v121
	v_cvt_pk_bf16_f32 v138, v122, v86
	v_cvt_pk_bf16_f32 v139, v123, v87
	v_cvt_pk_bf16_f32 v140, v120, v82
	v_cvt_pk_bf16_f32 v141, v121, v83
	v_addc_co_u32_e32 v147, vcc, 0, v147, vcc
	v_cvt_pk_bf16_f32 v142, v84, v78
	v_cvt_pk_bf16_f32 v143, v85, v79
	v_cvt_pk_bf16_f32 v144, v80, v76
	v_cvt_pk_bf16_f32 v145, v81, v77
	global_store_dwordx4 v[146:147], v[138:141], off
	global_store_dwordx4 v[146:147], v[142:145], off offset:16
	s_and_saveexec_b64 s[26:27], s[40:41]
	s_cbranch_execz .LBB0_208
	v_lshl_add_u64 v[142:143], s[10:11], 0, v[2:3]
	v_add_co_u32_e32 v142, vcc, 0x32000000, v142
	v_mov_b32_e32 v138, v122
	v_mov_b32_e32 v139, v86
	v_mov_b32_e32 v140, v123
	v_mov_b32_e32 v141, v87
	v_addc_co_u32_e32 v143, vcc, 0, v143, vcc
	global_store_dwordx4 v[142:143], v[138:141], off
	s_nop 1
	v_mov_b32_e32 v138, v120
	v_mov_b32_e32 v139, v82
	v_mov_b32_e32 v140, v121
	v_mov_b32_e32 v141, v83
	global_store_dwordx4 v[142:143], v[138:141], off offset:16
	s_nop 1
	v_mov_b32_e32 v138, v84
	v_mov_b32_e32 v139, v78
	v_mov_b32_e32 v140, v85
	v_mov_b32_e32 v141, v79
	global_store_dwordx4 v[142:143], v[138:141], off offset:32
	s_nop 1
	v_mov_b32_e32 v138, v80
	v_mov_b32_e32 v139, v76
	v_mov_b32_e32 v140, v81
	v_mov_b32_e32 v141, v77
	global_store_dwordx4 v[142:143], v[138:141], off offset:48
	s_branch .LBB0_208
